# slc tile loop: loop-invariant address arithmetic hoisted (4 VALU fewer per tile)
# speedup vs baseline: 1.0057x; 1.0057x over previous
; DI float bf2f(bf16 b) { return __uint_as_float(((unsigned)b) << 16); }
; DI void nsa_unit(const Ctx& c0, int b, int g, int i, LAS unsigned char* lds) {
;     ...
;     bf16x8 qr[4];
;     { const float* ct = (const float*)(c.ws + O_TAB) + (size_t)t * 32; const float* stb = ct + 4096 * 32;
; #pragma unroll
;       for (int s = 0; s < 2; ++s) {
;           const f32x4 c0 = *(const f32x4*)(ct + 16 * s + 8 * hi), c1 = *(const f32x4*)(ct + 16 * s + 8 * hi + 4);
;           const f32x4 s0 = *(const f32x4*)(stb + 16 * s + 8 * hi), s1 = *(const f32x4*)(stb + 16 * s + 8 * hi + 4);
;           float lo_[8], hi_[8], ol[8], oh[8];
; #pragma unroll
;           for (int j = 0; j < 8; ++j) { lo_[j] = bf2f((bf16)qn[s][j]); hi_[j] = bf2f((bf16)qn[s + 2][j]); }
; #pragma unroll
;           for (int j = 0; j < 8; ++j) { const float cc = j < 4 ? c0[j & 3] : c1[j & 3], ss = j < 4 ? s0[j & 3] : s1[j & 3];
;               ol[j] = lo_[j] * cc - hi_[j] * ss; oh[j] = hi_[j] * cc + lo_[j] * ss; }
;           qr[s] = pack8(ol[0], ol[1], ol[2], ol[3], ol[4], ol[5], ol[6], ol[7]); qr[s + 2] = pack8(oh[0], oh[1], oh[2], oh[3], oh[4], oh[5], oh[6], oh[7]); } }
;     ...
;     {
;         const bf16* Kg = (const bf16*)(c.ws + O_KS) + ((size_t)g * T + (size_t)b * SEQ) * 64;
;         const bf16* Vg = (const bf16*)(c.ws + O_VS) + ((size_t)g * T + (size_t)b * SEQ) * 64;
;         ASt st; st.m = NEGB; st.l = 0.f; st.o0 = f32x16{}; st.o1 = f32x16{};
;         unsigned long long rem = um;
;         int n = __builtin_ctzll(rem); rem &= rem - 1ull;
;         TileRegs tr = tile_fetch(Kg, Vg, 64 * n, tid);
.LBB0_565:
	v_lshlrev_b64 v[4:5], 7, v[2:3]
	v_lshl_add_u64 v[4:5], s[0:1], 0, v[4:5]
	v_lshlrev_b32_e32 v2, 2, v124
	v_lshl_add_u64 v[16:17], v[4:5], 0, v[2:3]
	s_mov_b64 s[12:13], 0x2200000
	v_add_co_u32_e32 v4, vcc, 0x2200000, v16
	v_lshl_add_u64 v[24:25], v[16:17], 0, s[12:13]
	s_mov_b64 s[12:13], 0x2280000
	v_addc_co_u32_e32 v5, vcc, 0, v17, vcc
	v_lshl_add_u64 v[14:15], v[16:17], 0, s[12:13]
	v_add_co_u32_e32 v16, vcc, 0x2280000, v16
	global_load_dwordx4 v[4:7], v[4:5], off
	s_nop 0
	global_load_dwordx4 v[8:11], v[24:25], off offset:16
	v_addc_co_u32_e32 v17, vcc, 0, v17, vcc
	global_load_dwordx4 v[16:19], v[16:17], off
	s_nop 0
	global_load_dwordx4 v[20:23], v[14:15], off offset:16
	global_load_dwordx4 v[230:233], v[24:25], off offset:64
	global_load_dwordx4 v[234:237], v[24:25], off offset:80
	global_load_dwordx4 v[238:241], v[14:15], off offset:64
	global_load_dwordx4 v[242:245], v[14:15], off offset:80
	v_and_b32_e32 v29, 0xffff0000, v108
	v_lshlrev_b32_e32 v28, 16, v108
	v_and_b32_e32 v27, 0xffff0000, v112
	v_lshlrev_b32_e32 v26, 16, v112
	v_ffbl_b32_e32 v2, v13
	s_add_u32 s12, s0, s94
	v_add_u32_e32 v2, 32, v2
	s_addc_u32 s13, s1, s95
	s_add_u32 s88, s12, 0x8400000
	s_addc_u32 s89, s13, 0
	s_add_u32 s90, s12, 0x9400000
	s_addc_u32 s91, s13, 0
	s_mov_b32 s3, 0
	s_mov_b64 s[12:13], 0
	v_ffbl_b32_e32 v246, v12
	v_min_u32_e32 v52, v246, v2
	v_lshl_add_u32 v246, v52, 6, v140
	v_ashrrev_i32_e32 v247, 31, v246
	v_lshlrev_b64 v[246:247], 7, v[246:247]
	v_lshl_or_b32 v246, v138, 1, v246
	v_lshl_add_u64 v[248:249], s[88:89], 0, v[246:247]
	v_lshl_add_u64 v[246:247], s[90:91], 0, v[246:247]
	global_load_dwordx4 v[54:57], v[248:249], off
	global_load_dwordx4 v[58:61], v[246:247], off
	s_waitcnt vmcnt(6) lgkmcnt(0)
	v_pk_mul_f32 v[30:31], v[16:17], v[28:29]
	s_nop 0
	v_pk_fma_f32 v[30:31], v[4:5], v[26:27], v[30:31] neg_lo:[0,0,1] neg_hi:[0,0,1]
	v_pk_mul_f32 v[16:17], v[16:17], v[26:27]
	v_and_b32_e32 v27, 0xffff0000, v109
	v_lshlrev_b32_e32 v26, 16, v109
	v_pk_fma_f32 v[4:5], v[4:5], v[28:29], v[16:17]
	v_and_b32_e32 v17, 0xffff0000, v113
	v_lshlrev_b32_e32 v16, 16, v113
	v_pk_mul_f32 v[28:29], v[18:19], v[26:27]
	v_cvt_pk_bf16_f32 v86, v4, v5
	v_pk_fma_f32 v[28:29], v[6:7], v[16:17], v[28:29] neg_lo:[0,0,1] neg_hi:[0,0,1]
	v_pk_mul_f32 v[16:17], v[18:19], v[16:17]
	v_and_b32_e32 v19, 0xffff0000, v110
	v_lshlrev_b32_e32 v18, 16, v110
	v_pk_fma_f32 v[6:7], v[6:7], v[26:27], v[16:17]
	v_and_b32_e32 v17, 0xffff0000, v114
	v_lshlrev_b32_e32 v16, 16, v114
	v_pk_mul_f32 v[26:27], v[20:21], v[18:19]
	v_cvt_pk_bf16_f32 v87, v6, v7
	v_pk_fma_f32 v[26:27], v[8:9], v[16:17], v[26:27] neg_lo:[0,0,1] neg_hi:[0,0,1]
	v_pk_mul_f32 v[16:17], v[20:21], v[16:17]
	v_cvt_pk_bf16_f32 v84, v26, v27
	v_pk_fma_f32 v[8:9], v[8:9], v[18:19], v[16:17]
	v_and_b32_e32 v19, 0xffff0000, v111
	v_lshlrev_b32_e32 v18, 16, v111
	v_and_b32_e32 v17, 0xffff0000, v115
	v_lshlrev_b32_e32 v16, 16, v115
	v_pk_mul_f32 v[20:21], v[22:23], v[18:19]
	v_cvt_pk_bf16_f32 v88, v8, v9
	v_pk_fma_f32 v[20:21], v[10:11], v[16:17], v[20:21] neg_lo:[0,0,1] neg_hi:[0,0,1]
	v_pk_mul_f32 v[16:17], v[22:23], v[16:17]
	v_cvt_pk_bf16_f32 v85, v20, v21
	v_pk_fma_f32 v[10:11], v[10:11], v[18:19], v[16:17]
	v_cvt_pk_bf16_f32 v82, v30, v31
	v_cvt_pk_bf16_f32 v89, v10, v11
	v_and_b32_e32 v25, 0xffff0000, v104
	v_lshlrev_b32_e32 v24, 16, v104
	v_and_b32_e32 v15, 0xffff0000, v100
	v_lshlrev_b32_e32 v14, 16, v100
	v_cvt_pk_bf16_f32 v83, v28, v29
	s_waitcnt vmcnt(2) lgkmcnt(0)
	v_pk_mul_f32 v[26:27], v[238:239], v[24:25]
	s_nop 0
	v_pk_fma_f32 v[26:27], v[230:231], v[14:15], v[26:27] neg_lo:[0, 0, 1] neg_hi:[0, 0, 1]
	v_pk_mul_f32 v[14:15], v[238:239], v[14:15]
	v_and_b32_e32 v17, 0xffff0000, v105
	v_lshlrev_b32_e32 v16, 16, v105
	v_pk_fma_f32 v[8:9], v[230:231], v[24:25], v[14:15]
	v_and_b32_e32 v15, 0xffff0000, v101
	v_lshlrev_b32_e32 v14, 16, v101
	v_pk_mul_f32 v[24:25], v[240:241], v[16:17]
	v_cvt_pk_bf16_f32 v90, v26, v27
	v_pk_fma_f32 v[24:25], v[232:233], v[14:15], v[24:25] neg_lo:[0, 0, 1] neg_hi:[0, 0, 1]
	v_pk_mul_f32 v[14:15], v[240:241], v[14:15]
	v_cvt_pk_bf16_f32 v91, v24, v25
	v_pk_fma_f32 v[10:11], v[232:233], v[16:17], v[14:15]
	v_and_b32_e32 v17, 0xffff0000, v106
	v_lshlrev_b32_e32 v16, 16, v106
	v_and_b32_e32 v15, 0xffff0000, v102
	v_lshlrev_b32_e32 v14, 16, v102
	v_pk_mul_f32 v[18:19], v[242:243], v[16:17]
	v_cvt_pk_bf16_f32 v94, v8, v9
	v_pk_fma_f32 v[18:19], v[234:235], v[14:15], v[18:19] neg_lo:[0, 0, 1] neg_hi:[0, 0, 1]
	v_pk_mul_f32 v[14:15], v[242:243], v[14:15]
	v_cvt_pk_bf16_f32 v92, v18, v19
	v_pk_fma_f32 v[4:5], v[234:235], v[16:17], v[14:15]
	v_and_b32_e32 v17, 0xffff0000, v107
	v_cvt_pk_bf16_f32 v96, v4, v5
	v_lshl_add_u64 v[4:5], v[12:13], 0, -1
	v_lshlrev_b32_e32 v16, 16, v107
	v_and_b32_e32 v50, v4, v12
	v_and_b32_e32 v15, 0xffff0000, v103
	v_lshlrev_b32_e32 v14, 16, v103
	v_pk_mul_f32 v[20:21], v[244:245], v[16:17]
	v_and_b32_e32 v51, v5, v13
	v_pk_fma_f32 v[20:21], v[236:237], v[14:15], v[20:21] neg_lo:[0, 0, 1] neg_hi:[0, 0, 1]
	v_pk_mul_f32 v[14:15], v[244:245], v[14:15]
	v_pk_fma_f32 v[6:7], v[236:237], v[16:17], v[14:15]
	v_cvt_pk_bf16_f32 v97, v6, v7
	v_mov_b32_e32 v16, v3
	v_mov_b32_e32 v17, v3
	v_cvt_pk_bf16_f32 v93, v20, v21
	v_cvt_pk_bf16_f32 v95, v10, v11
	v_mov_b32_e32 v2, v3
	v_mov_b32_e32 v4, v3
	v_mov_b32_e32 v5, v3
	v_mov_b32_e32 v6, v3
	v_mov_b32_e32 v7, v3
	v_mov_b32_e32 v8, v3
	v_mov_b32_e32 v9, v3
	v_mov_b32_e32 v10, v3
	v_mov_b32_e32 v11, v3
	v_mov_b32_e32 v12, v3
	v_mov_b32_e32 v13, v3
	v_mov_b32_e32 v14, v3
	v_mov_b32_e32 v15, v3
	v_mov_b64_e32 v[32:33], v[16:17]
	v_mov_b64_e32 v[48:49], v[16:17]
	v_mov_b32_e32 v107, 0xf149f2ca
	v_mov_b32_e32 v106, 0
	v_mov_b64_e32 v[30:31], v[14:15]
	v_mov_b64_e32 v[28:29], v[12:13]
	v_mov_b64_e32 v[26:27], v[10:11]
	v_mov_b64_e32 v[24:25], v[8:9]
	v_mov_b64_e32 v[22:23], v[6:7]
	v_mov_b64_e32 v[20:21], v[4:5]
	v_mov_b64_e32 v[18:19], v[2:3]
	v_mov_b64_e32 v[46:47], v[14:15]
	v_mov_b64_e32 v[44:45], v[12:13]
	v_mov_b64_e32 v[42:43], v[10:11]
	v_mov_b64_e32 v[40:41], v[8:9]
	v_mov_b64_e32 v[38:39], v[6:7]
	v_mov_b64_e32 v[36:37], v[4:5]
	v_mov_b64_e32 v[34:35], v[2:3]
	s_waitcnt vmcnt(0)
	v_mov_b64_e32 v[98:99], v[54:55]
	v_mov_b64_e32 v[100:101], v[56:57]
	v_mov_b64_e32 v[102:103], v[58:59]
	v_mov_b64_e32 v[104:105], v[60:61]
	v_readfirstlane_b32 s98, v50
	v_readfirstlane_b32 s99, v51
	v_readfirstlane_b32 s100, v52
	v_add3_u32 v247, v227, v228, v229
	v_lshlrev_b32_e32 v246, 7, v140
	v_lshl_or_b32 v246, v138, 1, v246
	v_add3_u32 v248, v208, v209, v197
	v_add_u32_e32 v248, v248, v198
	s_branch .LBB0_568

; #define LAS __attribute__((address_space(3)))
; #define LDS_WAIT() asm volatile("s_waitcnt lgkmcnt(0)" ::: "memory")
; #define MFMA32(a, b, c) __builtin_amdgcn_mfma_f32_32x32x16_bf16((a), (b), (c), 0, 0, 0)
; DI s16x4 vtr(const LAS unsigned char* p) { return __builtin_bit_cast(s16x4, __builtin_amdgcn_ds_read_tr16_b64_v4i16((LAS v4i16_t*)p)); }
; template <bool CMP> DI void tile_compute(LAS unsigned char* lds, int buf, const bf16x8 (&q)[4], int lo, int hv, ASt& st, f32x16& imp0, f32x16& imp1, int jt, LAS float* wsf, int lane) {
;     ...
;     float sum = 0.f;
;     const float msub = (!anyPart && dead) ? 1e30f : mnew;
; #pragma unroll
;     for (int rg = 0; rg < 16; ++rg) { p0[rg] = __builtin_amdgcn_exp2f(p0[rg] - msub); p1[rg] = __builtin_amdgcn_exp2f(p1[rg] - msub); sum += p0[rg] + p1[rg]; }
;     st.l = st.l * alpha + sum;
;     if (__builtin_amdgcn_ballot_w64(alpha != 1.f) != 0ull) {
;         if (hi == 0) wsf[r] = alpha;
;         LDS_WAIT();
; #pragma unroll
;         for (int g4 = 0; g4 < 4; ++g4) { const f32x4 f = *(const LAS f32x4*)(wsf + 8 * g4 + 4 * hi);
; #pragma unroll
;             for (int k = 0; k < 4; ++k) { st.o0[4 * g4 + k] *= f[k]; st.o1[4 * g4 + k] *= f[k]; if (CMP) { imp0[4 * g4 + k] *= f[k]; imp1[4 * g4 + k] *= f[k]; } } }
;         LDS_WAIT();
;     }
;     bf16x8 pa[4];
;     pa[0] = pack8(p0[0], p0[1], p0[2], p0[3], p0[4], p0[5], p0[6], p0[7]); pa[1] = pack8(p0[8], p0[9], p0[10], p0[11], p0[12], p0[13], p0[14], p0[15]);
;     pa[2] = pack8(p1[0], p1[1], p1[2], p1[3], p1[4], p1[5], p1[6], p1[7]); pa[3] = pack8(p1[8], p1[9], p1[10], p1[11], p1[12], p1[13], p1[14], p1[15]);
;     const LAS unsigned char* vb = lds + A_VT + buf * 8192 + (4 * hi + ((lane & 15) >> 2)) * 64 + ((lane >> 4) & 1) * 32 + (lane & 3) * 8;
; #pragma unroll
;     for (int s = 0; s < 4; ++s) {
;         const bf16x8 v0 = cat8(vtr(vb + s * 1024), vtr(vb + s * 1024 + 512));
;         const bf16x8 v1 = cat8(vtr(vb + 4096 + s * 1024), vtr(vb + 4096 + s * 1024 + 512));
;         st.o0 = MFMA32(pa[s], v0, st.o0); st.o1 = MFMA32(pa[s], v1, st.o1);
;     }
; DI void nsa_unit(const Ctx& c0, int b, int g, int i, LAS unsigned char* lds) {
;     ...
;             tile_stage(tr, lds, k & 1, tid);
;             __syncthreads();
;             const bool more = rem != 0ull; int nn = 0;
;             if (more) { nn = __builtin_ctzll(rem); rem &= rem - 1ull; tr = tile_fetch(Kg, Vg, 64 * nn, tid); }
.LBB0_567:
	s_and_b64 s[14:15], exec, s[78:79]
	s_or_b64 s[12:13], s[14:15], s[12:13]
	s_addk_i32 s3, 0x2000
	v_mul_f32_e32 v11, v106, v4
	v_add_u32_e32 v16, s84, v248
	ds_read_b64_tr_b16 v[108:109], v16 offset:16384
	ds_read_b64_tr_b16 v[110:111], v16 offset:16896
	ds_read_b64_tr_b16 v[112:113], v16 offset:20480
	ds_read_b64_tr_b16 v[114:115], v16 offset:20992
	ds_read_b64_tr_b16 v[120:121], v16 offset:17408
	ds_read_b64_tr_b16 v[122:123], v16 offset:17920
	v_cndmask_b32_e64 v12, v2, v223, s[80:81]
	v_mov_b32_e32 v13, v12
	v_pk_add_f32 v[66:67], v[66:67], v[12:13] neg_lo:[0,1] neg_hi:[0,1]
	v_pk_add_f32 v[68:69], v[68:69], v[12:13] neg_lo:[0,1] neg_hi:[0,1]
	v_pk_add_f32 v[70:71], v[70:71], v[12:13] neg_lo:[0,1] neg_hi:[0,1]
	v_pk_add_f32 v[72:73], v[72:73], v[12:13] neg_lo:[0,1] neg_hi:[0,1]
	v_pk_add_f32 v[74:75], v[74:75], v[12:13] neg_lo:[0,1] neg_hi:[0,1]
	v_pk_add_f32 v[76:77], v[76:77], v[12:13] neg_lo:[0,1] neg_hi:[0,1]
	v_pk_add_f32 v[78:79], v[78:79], v[12:13] neg_lo:[0,1] neg_hi:[0,1]
	v_pk_add_f32 v[80:81], v[80:81], v[12:13] neg_lo:[0,1] neg_hi:[0,1]
	v_exp_f32_e32 v66, v66
	v_exp_f32_e32 v67, v67
	v_exp_f32_e32 v68, v68
	v_exp_f32_e32 v69, v69
	v_exp_f32_e32 v70, v70
	v_exp_f32_e32 v71, v71
	v_exp_f32_e32 v72, v72
	v_exp_f32_e32 v73, v73
	v_exp_f32_e32 v74, v74
	v_exp_f32_e32 v75, v75
	v_exp_f32_e32 v76, v76
	v_exp_f32_e32 v77, v77
	v_exp_f32_e32 v78, v78
	v_exp_f32_e32 v79, v79
	v_exp_f32_e32 v80, v80
	v_exp_f32_e32 v81, v81
	v_pk_add_f32 v[14:15], v[66:67], v[68:69]
	v_pk_add_f32 v[14:15], v[14:15], v[70:71]
	v_pk_add_f32 v[14:15], v[14:15], v[72:73]
	v_cvt_pk_bf16_f32 v66, v66, v67
	v_cvt_pk_bf16_f32 v67, v68, v69
	v_cvt_pk_bf16_f32 v68, v70, v71
	v_cvt_pk_bf16_f32 v69, v72, v73
	ds_read_b64_tr_b16 v[70:71], v16 offset:21504
	ds_read_b64_tr_b16 v[72:73], v16 offset:22016
	v_pk_add_f32 v[14:15], v[14:15], v[74:75]
	v_pk_add_f32 v[14:15], v[14:15], v[76:77]
	v_pk_add_f32 v[14:15], v[14:15], v[78:79]
	v_pk_add_f32 v[14:15], v[14:15], v[80:81]
	v_cvt_pk_bf16_f32 v74, v74, v75
	v_cvt_pk_bf16_f32 v75, v76, v77
	v_cvt_pk_bf16_f32 v76, v78, v79
	v_cvt_pk_bf16_f32 v77, v80, v81
	ds_read_b64_tr_b16 v[78:79], v16 offset:18432
	ds_read_b64_tr_b16 v[80:81], v16 offset:18944
	s_waitcnt lgkmcnt(8)
	v_mfma_f32_32x32x16_bf16 v[34:49], v[66:69], v[108:111], v[34:49]
	ds_read_b64_tr_b16 v[108:109], v16 offset:23552
	ds_read_b64_tr_b16 v[110:111], v16 offset:24064
	v_pk_add_f32 v[50:51], v[50:51], v[12:13] neg_lo:[0,1] neg_hi:[0,1]
	v_pk_add_f32 v[52:53], v[52:53], v[12:13] neg_lo:[0,1] neg_hi:[0,1]
	v_pk_add_f32 v[54:55], v[54:55], v[12:13] neg_lo:[0,1] neg_hi:[0,1]
	v_pk_add_f32 v[56:57], v[56:57], v[12:13] neg_lo:[0,1] neg_hi:[0,1]
	s_waitcnt lgkmcnt(8)
	v_mfma_f32_32x32x16_bf16 v[18:33], v[66:69], v[112:115], v[18:33]
	ds_read_b64_tr_b16 v[112:113], v16 offset:22528
	ds_read_b64_tr_b16 v[114:115], v16 offset:23040
	v_pk_add_f32 v[58:59], v[58:59], v[12:13] neg_lo:[0,1] neg_hi:[0,1]
	v_pk_add_f32 v[60:61], v[60:61], v[12:13] neg_lo:[0,1] neg_hi:[0,1]
	v_pk_add_f32 v[62:63], v[62:63], v[12:13] neg_lo:[0,1] neg_hi:[0,1]
	v_pk_add_f32 v[64:65], v[64:65], v[12:13] neg_lo:[0,1] neg_hi:[0,1]
	v_exp_f32_e32 v50, v50
	v_exp_f32_e32 v51, v51
	v_exp_f32_e32 v52, v52
	v_exp_f32_e32 v53, v53
	v_exp_f32_e32 v54, v54
	s_waitcnt lgkmcnt(8)
	v_mfma_f32_32x32x16_bf16 v[34:49], v[74:77], v[120:123], v[34:49]
	ds_read_b64_tr_b16 v[120:121], v16 offset:19456
	ds_read_b64_tr_b16 v[122:123], v16 offset:19968
	v_exp_f32_e32 v55, v55
	v_exp_f32_e32 v56, v56
	v_exp_f32_e32 v57, v57
	v_exp_f32_e32 v58, v58
	v_exp_f32_e32 v59, v59
	v_exp_f32_e32 v60, v60
	s_waitcnt lgkmcnt(8)
	v_mfma_f32_32x32x16_bf16 v[18:33], v[74:77], v[70:73], v[18:33]
	v_exp_f32_e32 v61, v61
	v_exp_f32_e32 v62, v62
	v_exp_f32_e32 v63, v63
	v_exp_f32_e32 v64, v64
	v_exp_f32_e32 v65, v65
	v_pk_add_f32 v[14:15], v[14:15], v[50:51]
	v_pk_add_f32 v[14:15], v[14:15], v[52:53]
	v_pk_add_f32 v[14:15], v[14:15], v[54:55]
	v_pk_add_f32 v[14:15], v[14:15], v[56:57]
	v_cvt_pk_bf16_f32 v50, v50, v51
	v_cvt_pk_bf16_f32 v51, v52, v53
	v_cvt_pk_bf16_f32 v52, v54, v55
	v_cvt_pk_bf16_f32 v53, v56, v57
	v_pk_add_f32 v[14:15], v[14:15], v[58:59]
	v_pk_add_f32 v[14:15], v[14:15], v[60:61]
	s_waitcnt lgkmcnt(6)
	v_mfma_f32_32x32x16_bf16 v[34:49], v[50:53], v[78:81], v[34:49]
	v_pk_add_f32 v[14:15], v[14:15], v[62:63]
	v_pk_add_f32 v[14:15], v[14:15], v[64:65]
	v_cvt_pk_bf16_f32 v58, v58, v59
	v_cvt_pk_bf16_f32 v59, v60, v61
	v_cvt_pk_bf16_f32 v60, v62, v63
	v_cvt_pk_bf16_f32 v61, v64, v65
	v_add_f32_e32 v11, v11, v14
	v_add_f32_e32 v11, v11, v15
	v_mov_b32_e32 v106, v11
	v_mov_b32_e32 v107, v2
	s_waitcnt lgkmcnt(2)
	v_mfma_f32_32x32x16_bf16 v[18:33], v[50:53], v[112:115], v[18:33]
	s_waitcnt lgkmcnt(0)
	v_mfma_f32_32x32x16_bf16 v[34:49], v[58:61], v[120:123], v[34:49]
	v_mfma_f32_32x32x16_bf16 v[18:33], v[58:61], v[108:111], v[18:33]
	s_mov_b32 s100, s101
	s_andn2_b64 exec, exec, s[12:13]
	s_cbranch_execz .LBB0_575
.LBB0_568:
	s_and_b32 s14, s3, 0x2000
	s_add_i32 s84, s14, 0
	v_add3_u32 v2, s84, v225, v226
	s_waitcnt vmcnt(0) lgkmcnt(0)
	ds_write_b128 v2, v[98:101]
	v_add_u32_e32 v2, s84, v247
	s_cmp_eq_u64 s[98:99], 0
	s_cselect_b64 s[78:79], -1, 0
	s_cselect_b64 vcc, 0, -1
	ds_write_b128 v2, v[102:105] offset:16384
	s_waitcnt lgkmcnt(0)
	s_barrier
	s_and_saveexec_b64 s[14:15], vcc
	s_cbranch_execz .LBB0_570
	s_ff1_i32_b64 s101, s[98:99]
	s_add_u32 s80, s98, -1
	s_addc_u32 s81, s99, -1
	s_and_b64 s[98:99], s[98:99], s[80:81]
	s_lshl_b32 s82, s101, 13
	s_add_u32 s80, s88, s82
	s_addc_u32 s81, s89, 0
	s_add_u32 s82, s90, s82
	s_addc_u32 s83, s91, 0
	global_load_dwordx4 v[98:101], v246, s[80:81]
	global_load_dwordx4 v[102:105], v246, s[82:83]

; DI float bf2f(bf16 b) { return __uint_as_float(((unsigned)b) << 16); }
; DI void nsa_unit(const Ctx& c0, int b, int g, int i, LAS unsigned char* lds) {
;     ...
;     bf16x8 qr[4];
;     { const float* ct = (const float*)(c.ws + O_TAB) + (size_t)t * 32; const float* stb = ct + 4096 * 32;
; #pragma unroll
;       for (int s = 0; s < 2; ++s) {
;           const f32x4 c0 = *(const f32x4*)(ct + 16 * s + 8 * hi), c1 = *(const f32x4*)(ct + 16 * s + 8 * hi + 4);
;           const f32x4 s0 = *(const f32x4*)(stb + 16 * s + 8 * hi), s1 = *(const f32x4*)(stb + 16 * s + 8 * hi + 4);
;           float lo_[8], hi_[8], ol[8], oh[8];
; #pragma unroll
;           for (int j = 0; j < 8; ++j) { lo_[j] = bf2f((bf16)qn[s][j]); hi_[j] = bf2f((bf16)qn[s + 2][j]); }
; #pragma unroll
;           for (int j = 0; j < 8; ++j) { const float cc = j < 4 ? c0[j & 3] : c1[j & 3], ss = j < 4 ? s0[j & 3] : s1[j & 3];
;               ol[j] = lo_[j] * cc - hi_[j] * ss; oh[j] = hi_[j] * cc + lo_[j] * ss; }
;           qr[s] = pack8(ol[0], ol[1], ol[2], ol[3], ol[4], ol[5], ol[6], ol[7]); qr[s + 2] = pack8(oh[0], oh[1], oh[2], oh[3], oh[4], oh[5], oh[6], oh[7]); } }
;     ...
;     {
;         const bf16* Kg = (const bf16*)(c.ws + O_KS) + ((size_t)g * T + (size_t)b * SEQ) * 64;
;         const bf16* Vg = (const bf16*)(c.ws + O_VS) + ((size_t)g * T + (size_t)b * SEQ) * 64;
;         ASt st; st.m = NEGB; st.l = 0.f; st.o0 = f32x16{}; st.o1 = f32x16{};
;         unsigned long long rem = um;
;         int n = __builtin_ctzll(rem); rem &= rem - 1ull;
;         TileRegs tr = tile_fetch(Kg, Vg, 64 * n, tid);
.LBB0_1178:
	v_lshlrev_b64 v[4:5], 7, v[2:3]
	v_lshl_add_u64 v[4:5], s[0:1], 0, v[4:5]
	v_lshlrev_b32_e32 v2, 2, v124
	v_lshl_add_u64 v[16:17], v[4:5], 0, v[2:3]
	s_mov_b64 s[14:15], 0x2200000
	v_add_co_u32_e32 v4, vcc, 0x2200000, v16
	v_lshl_add_u64 v[24:25], v[16:17], 0, s[14:15]
	s_mov_b64 s[14:15], 0x2280000
	v_addc_co_u32_e32 v5, vcc, 0, v17, vcc
	v_lshl_add_u64 v[14:15], v[16:17], 0, s[14:15]
	v_add_co_u32_e32 v16, vcc, 0x2280000, v16
	global_load_dwordx4 v[4:7], v[4:5], off
	s_nop 0
	global_load_dwordx4 v[8:11], v[24:25], off offset:16
	v_addc_co_u32_e32 v17, vcc, 0, v17, vcc
	global_load_dwordx4 v[16:19], v[16:17], off
	s_nop 0
	global_load_dwordx4 v[20:23], v[14:15], off offset:16
	global_load_dwordx4 v[230:233], v[24:25], off offset:64
	global_load_dwordx4 v[234:237], v[24:25], off offset:80
	global_load_dwordx4 v[238:241], v[14:15], off offset:64
	global_load_dwordx4 v[242:245], v[14:15], off offset:80
	v_and_b32_e32 v29, 0xffff0000, v108
	v_lshlrev_b32_e32 v28, 16, v108
	v_and_b32_e32 v27, 0xffff0000, v112
	v_lshlrev_b32_e32 v26, 16, v112
	v_ffbl_b32_e32 v2, v13
	s_add_u32 s14, s0, s2
	v_add_u32_e32 v2, 32, v2
	s_addc_u32 s15, s1, s3
	s_add_u32 s88, s14, 0x8400000
	s_addc_u32 s89, s15, 0
	s_add_u32 s90, s14, 0x9400000
	s_addc_u32 s91, s15, 0
	s_mov_b32 s6, 0
	s_mov_b64 s[14:15], 0
	v_ffbl_b32_e32 v246, v12
	v_min_u32_e32 v52, v246, v2
	v_lshl_add_u32 v246, v52, 6, v140
	v_ashrrev_i32_e32 v247, 31, v246
	v_lshlrev_b64 v[246:247], 7, v[246:247]
	v_lshl_or_b32 v246, v138, 1, v246
	v_lshl_add_u64 v[248:249], s[88:89], 0, v[246:247]
	v_lshl_add_u64 v[246:247], s[90:91], 0, v[246:247]
	global_load_dwordx4 v[54:57], v[248:249], off
	global_load_dwordx4 v[58:61], v[246:247], off
	s_waitcnt vmcnt(6) lgkmcnt(0)
	v_pk_mul_f32 v[30:31], v[16:17], v[28:29]
	s_nop 0
	v_pk_fma_f32 v[30:31], v[4:5], v[26:27], v[30:31] neg_lo:[0,0,1] neg_hi:[0,0,1]
	v_pk_mul_f32 v[16:17], v[16:17], v[26:27]
	v_and_b32_e32 v27, 0xffff0000, v109
	v_lshlrev_b32_e32 v26, 16, v109
	v_pk_fma_f32 v[4:5], v[4:5], v[28:29], v[16:17]
	v_and_b32_e32 v17, 0xffff0000, v113
	v_lshlrev_b32_e32 v16, 16, v113
	v_pk_mul_f32 v[28:29], v[18:19], v[26:27]
	v_cvt_pk_bf16_f32 v86, v4, v5
	v_pk_fma_f32 v[28:29], v[6:7], v[16:17], v[28:29] neg_lo:[0,0,1] neg_hi:[0,0,1]
	v_pk_mul_f32 v[16:17], v[18:19], v[16:17]
	v_and_b32_e32 v19, 0xffff0000, v110
	v_lshlrev_b32_e32 v18, 16, v110
	v_pk_fma_f32 v[6:7], v[6:7], v[26:27], v[16:17]
	v_and_b32_e32 v17, 0xffff0000, v114
	v_lshlrev_b32_e32 v16, 16, v114
	v_pk_mul_f32 v[26:27], v[20:21], v[18:19]
	v_cvt_pk_bf16_f32 v87, v6, v7
	v_pk_fma_f32 v[26:27], v[8:9], v[16:17], v[26:27] neg_lo:[0,0,1] neg_hi:[0,0,1]
	v_pk_mul_f32 v[16:17], v[20:21], v[16:17]
	v_cvt_pk_bf16_f32 v84, v26, v27
	v_pk_fma_f32 v[8:9], v[8:9], v[18:19], v[16:17]
	v_and_b32_e32 v19, 0xffff0000, v111
	v_lshlrev_b32_e32 v18, 16, v111
	v_and_b32_e32 v17, 0xffff0000, v115
	v_lshlrev_b32_e32 v16, 16, v115
	v_pk_mul_f32 v[20:21], v[22:23], v[18:19]
	v_cvt_pk_bf16_f32 v88, v8, v9
	v_pk_fma_f32 v[20:21], v[10:11], v[16:17], v[20:21] neg_lo:[0,0,1] neg_hi:[0,0,1]
	v_pk_mul_f32 v[16:17], v[22:23], v[16:17]
	v_cvt_pk_bf16_f32 v85, v20, v21
	v_pk_fma_f32 v[10:11], v[10:11], v[18:19], v[16:17]
	v_cvt_pk_bf16_f32 v82, v30, v31
	v_cvt_pk_bf16_f32 v89, v10, v11
	v_and_b32_e32 v25, 0xffff0000, v104
	v_lshlrev_b32_e32 v24, 16, v104
	v_and_b32_e32 v15, 0xffff0000, v100
	v_lshlrev_b32_e32 v14, 16, v100
	v_cvt_pk_bf16_f32 v83, v28, v29
	s_waitcnt vmcnt(2) lgkmcnt(0)
	v_pk_mul_f32 v[26:27], v[238:239], v[24:25]
	s_nop 0
	v_pk_fma_f32 v[26:27], v[230:231], v[14:15], v[26:27] neg_lo:[0, 0, 1] neg_hi:[0, 0, 1]
	v_pk_mul_f32 v[14:15], v[238:239], v[14:15]
	v_and_b32_e32 v17, 0xffff0000, v105
	v_lshlrev_b32_e32 v16, 16, v105
	v_pk_fma_f32 v[8:9], v[230:231], v[24:25], v[14:15]
	v_and_b32_e32 v15, 0xffff0000, v101
	v_lshlrev_b32_e32 v14, 16, v101
	v_pk_mul_f32 v[24:25], v[240:241], v[16:17]
	v_cvt_pk_bf16_f32 v90, v26, v27
	v_pk_fma_f32 v[24:25], v[232:233], v[14:15], v[24:25] neg_lo:[0, 0, 1] neg_hi:[0, 0, 1]
	v_pk_mul_f32 v[14:15], v[240:241], v[14:15]
	v_cvt_pk_bf16_f32 v91, v24, v25
	v_pk_fma_f32 v[10:11], v[232:233], v[16:17], v[14:15]
	v_and_b32_e32 v17, 0xffff0000, v106
	v_lshlrev_b32_e32 v16, 16, v106
	v_and_b32_e32 v15, 0xffff0000, v102
	v_lshlrev_b32_e32 v14, 16, v102
	v_pk_mul_f32 v[18:19], v[242:243], v[16:17]
	v_cvt_pk_bf16_f32 v94, v8, v9
	v_pk_fma_f32 v[18:19], v[234:235], v[14:15], v[18:19] neg_lo:[0, 0, 1] neg_hi:[0, 0, 1]
	v_pk_mul_f32 v[14:15], v[242:243], v[14:15]
	v_cvt_pk_bf16_f32 v92, v18, v19
	v_pk_fma_f32 v[4:5], v[234:235], v[16:17], v[14:15]
	v_and_b32_e32 v17, 0xffff0000, v107
	v_cvt_pk_bf16_f32 v96, v4, v5
	v_lshl_add_u64 v[4:5], v[12:13], 0, -1
	v_lshlrev_b32_e32 v16, 16, v107
	v_and_b32_e32 v50, v4, v12
	v_and_b32_e32 v15, 0xffff0000, v103
	v_lshlrev_b32_e32 v14, 16, v103
	v_pk_mul_f32 v[20:21], v[244:245], v[16:17]
	v_and_b32_e32 v51, v5, v13
	v_pk_fma_f32 v[20:21], v[236:237], v[14:15], v[20:21] neg_lo:[0, 0, 1] neg_hi:[0, 0, 1]
	v_pk_mul_f32 v[14:15], v[244:245], v[14:15]
	v_pk_fma_f32 v[6:7], v[236:237], v[16:17], v[14:15]
	v_cvt_pk_bf16_f32 v97, v6, v7
	v_mov_b32_e32 v16, v3
	v_mov_b32_e32 v17, v3
	v_cvt_pk_bf16_f32 v93, v20, v21
	v_cvt_pk_bf16_f32 v95, v10, v11
	v_mov_b32_e32 v2, v3
	v_mov_b32_e32 v4, v3
	v_mov_b32_e32 v5, v3
	v_mov_b32_e32 v6, v3
	v_mov_b32_e32 v7, v3
	v_mov_b32_e32 v8, v3
	v_mov_b32_e32 v9, v3
	v_mov_b32_e32 v10, v3
	v_mov_b32_e32 v11, v3
	v_mov_b32_e32 v12, v3
	v_mov_b32_e32 v13, v3
	v_mov_b32_e32 v14, v3
	v_mov_b32_e32 v15, v3
	v_mov_b64_e32 v[32:33], v[16:17]
	v_mov_b64_e32 v[48:49], v[16:17]
	v_mov_b32_e32 v107, 0xf149f2ca
	v_mov_b32_e32 v106, 0
	v_mov_b64_e32 v[30:31], v[14:15]
	v_mov_b64_e32 v[28:29], v[12:13]
	v_mov_b64_e32 v[26:27], v[10:11]
	v_mov_b64_e32 v[24:25], v[8:9]
	v_mov_b64_e32 v[22:23], v[6:7]
	v_mov_b64_e32 v[20:21], v[4:5]
	v_mov_b64_e32 v[18:19], v[2:3]
	v_mov_b64_e32 v[46:47], v[14:15]
	v_mov_b64_e32 v[44:45], v[12:13]
	v_mov_b64_e32 v[42:43], v[10:11]
	v_mov_b64_e32 v[40:41], v[8:9]
	v_mov_b64_e32 v[38:39], v[6:7]
	v_mov_b64_e32 v[36:37], v[4:5]
	v_mov_b64_e32 v[34:35], v[2:3]
	s_waitcnt vmcnt(0)
	v_mov_b64_e32 v[98:99], v[54:55]
	v_mov_b64_e32 v[100:101], v[56:57]
	v_mov_b64_e32 v[102:103], v[58:59]
	v_mov_b64_e32 v[104:105], v[60:61]
	v_readfirstlane_b32 s98, v50
	v_readfirstlane_b32 s99, v51
	v_readfirstlane_b32 s100, v52
	v_add3_u32 v247, v222, v223, v224
	v_lshlrev_b32_e32 v246, 7, v140
	v_lshl_or_b32 v246, v138, 1, v246
	v_add3_u32 v248, v207, v191, v187
	v_add_u32_e32 v248, v248, v186
	s_branch .LBB0_1181

; #define LAS __attribute__((address_space(3)))
; #define LDS_WAIT() asm volatile("s_waitcnt lgkmcnt(0)" ::: "memory")
; #define MFMA32(a, b, c) __builtin_amdgcn_mfma_f32_32x32x16_bf16((a), (b), (c), 0, 0, 0)
; DI s16x4 vtr(const LAS unsigned char* p) { return __builtin_bit_cast(s16x4, __builtin_amdgcn_ds_read_tr16_b64_v4i16((LAS v4i16_t*)p)); }
; template <bool CMP> DI void tile_compute(LAS unsigned char* lds, int buf, const bf16x8 (&q)[4], int lo, int hv, ASt& st, f32x16& imp0, f32x16& imp1, int jt, LAS float* wsf, int lane) {
;     ...
;     float sum = 0.f;
;     const float msub = (!anyPart && dead) ? 1e30f : mnew;
; #pragma unroll
;     for (int rg = 0; rg < 16; ++rg) { p0[rg] = __builtin_amdgcn_exp2f(p0[rg] - msub); p1[rg] = __builtin_amdgcn_exp2f(p1[rg] - msub); sum += p0[rg] + p1[rg]; }
;     st.l = st.l * alpha + sum;
;     if (__builtin_amdgcn_ballot_w64(alpha != 1.f) != 0ull) {
;         if (hi == 0) wsf[r] = alpha;
;         LDS_WAIT();
; #pragma unroll
;         for (int g4 = 0; g4 < 4; ++g4) { const f32x4 f = *(const LAS f32x4*)(wsf + 8 * g4 + 4 * hi);
; #pragma unroll
;             for (int k = 0; k < 4; ++k) { st.o0[4 * g4 + k] *= f[k]; st.o1[4 * g4 + k] *= f[k]; if (CMP) { imp0[4 * g4 + k] *= f[k]; imp1[4 * g4 + k] *= f[k]; } } }
;         LDS_WAIT();
;     }
;     bf16x8 pa[4];
;     pa[0] = pack8(p0[0], p0[1], p0[2], p0[3], p0[4], p0[5], p0[6], p0[7]); pa[1] = pack8(p0[8], p0[9], p0[10], p0[11], p0[12], p0[13], p0[14], p0[15]);
;     pa[2] = pack8(p1[0], p1[1], p1[2], p1[3], p1[4], p1[5], p1[6], p1[7]); pa[3] = pack8(p1[8], p1[9], p1[10], p1[11], p1[12], p1[13], p1[14], p1[15]);
;     const LAS unsigned char* vb = lds + A_VT + buf * 8192 + (4 * hi + ((lane & 15) >> 2)) * 64 + ((lane >> 4) & 1) * 32 + (lane & 3) * 8;
; #pragma unroll
;     for (int s = 0; s < 4; ++s) {
;         const bf16x8 v0 = cat8(vtr(vb + s * 1024), vtr(vb + s * 1024 + 512));
;         const bf16x8 v1 = cat8(vtr(vb + 4096 + s * 1024), vtr(vb + 4096 + s * 1024 + 512));
;         st.o0 = MFMA32(pa[s], v0, st.o0); st.o1 = MFMA32(pa[s], v1, st.o1);
;     }
; DI void nsa_unit(const Ctx& c0, int b, int g, int i, LAS unsigned char* lds) {
;     ...
;             tile_stage(tr, lds, k & 1, tid);
;             __syncthreads();
;             const bool more = rem != 0ull; int nn = 0;
;             if (more) { nn = __builtin_ctzll(rem); rem &= rem - 1ull; tr = tile_fetch(Kg, Vg, 64 * nn, tid); }
.LBB0_1180:
	s_and_b64 s[16:17], exec, s[80:81]
	s_or_b64 s[14:15], s[16:17], s[14:15]
	s_addk_i32 s6, 0x2000
	v_mul_f32_e32 v11, v106, v4
	v_add_u32_e32 v16, s28, v248
	ds_read_b64_tr_b16 v[108:109], v16 offset:16384
	ds_read_b64_tr_b16 v[110:111], v16 offset:16896
	ds_read_b64_tr_b16 v[112:113], v16 offset:20480
	ds_read_b64_tr_b16 v[114:115], v16 offset:20992
	ds_read_b64_tr_b16 v[120:121], v16 offset:17408
	ds_read_b64_tr_b16 v[122:123], v16 offset:17920
	v_cndmask_b32_e64 v12, v2, v218, s[82:83]
	v_mov_b32_e32 v13, v12
	v_pk_add_f32 v[66:67], v[66:67], v[12:13] neg_lo:[0,1] neg_hi:[0,1]
	v_pk_add_f32 v[68:69], v[68:69], v[12:13] neg_lo:[0,1] neg_hi:[0,1]
	v_pk_add_f32 v[70:71], v[70:71], v[12:13] neg_lo:[0,1] neg_hi:[0,1]
	v_pk_add_f32 v[72:73], v[72:73], v[12:13] neg_lo:[0,1] neg_hi:[0,1]
	v_pk_add_f32 v[74:75], v[74:75], v[12:13] neg_lo:[0,1] neg_hi:[0,1]
	v_pk_add_f32 v[76:77], v[76:77], v[12:13] neg_lo:[0,1] neg_hi:[0,1]
	v_pk_add_f32 v[78:79], v[78:79], v[12:13] neg_lo:[0,1] neg_hi:[0,1]
	v_pk_add_f32 v[80:81], v[80:81], v[12:13] neg_lo:[0,1] neg_hi:[0,1]
	v_exp_f32_e32 v66, v66
	v_exp_f32_e32 v67, v67
	v_exp_f32_e32 v68, v68
	v_exp_f32_e32 v69, v69
	v_exp_f32_e32 v70, v70
	v_exp_f32_e32 v71, v71
	v_exp_f32_e32 v72, v72
	v_exp_f32_e32 v73, v73
	v_exp_f32_e32 v74, v74
	v_exp_f32_e32 v75, v75
	v_exp_f32_e32 v76, v76
	v_exp_f32_e32 v77, v77
	v_exp_f32_e32 v78, v78
	v_exp_f32_e32 v79, v79
	v_exp_f32_e32 v80, v80
	v_exp_f32_e32 v81, v81
	v_pk_add_f32 v[14:15], v[66:67], v[68:69]
	v_pk_add_f32 v[14:15], v[14:15], v[70:71]
	v_pk_add_f32 v[14:15], v[14:15], v[72:73]
	v_cvt_pk_bf16_f32 v66, v66, v67
	v_cvt_pk_bf16_f32 v67, v68, v69
	v_cvt_pk_bf16_f32 v68, v70, v71
	v_cvt_pk_bf16_f32 v69, v72, v73
	ds_read_b64_tr_b16 v[70:71], v16 offset:21504
	ds_read_b64_tr_b16 v[72:73], v16 offset:22016
	v_pk_add_f32 v[14:15], v[14:15], v[74:75]
	v_pk_add_f32 v[14:15], v[14:15], v[76:77]
	v_pk_add_f32 v[14:15], v[14:15], v[78:79]
	v_pk_add_f32 v[14:15], v[14:15], v[80:81]
	v_cvt_pk_bf16_f32 v74, v74, v75
	v_cvt_pk_bf16_f32 v75, v76, v77
	v_cvt_pk_bf16_f32 v76, v78, v79
	v_cvt_pk_bf16_f32 v77, v80, v81
	ds_read_b64_tr_b16 v[78:79], v16 offset:18432
	ds_read_b64_tr_b16 v[80:81], v16 offset:18944
	s_waitcnt lgkmcnt(8)
	v_mfma_f32_32x32x16_bf16 v[34:49], v[66:69], v[108:111], v[34:49]
	ds_read_b64_tr_b16 v[108:109], v16 offset:23552
	ds_read_b64_tr_b16 v[110:111], v16 offset:24064
	v_pk_add_f32 v[50:51], v[50:51], v[12:13] neg_lo:[0,1] neg_hi:[0,1]
	v_pk_add_f32 v[52:53], v[52:53], v[12:13] neg_lo:[0,1] neg_hi:[0,1]
	v_pk_add_f32 v[54:55], v[54:55], v[12:13] neg_lo:[0,1] neg_hi:[0,1]
	v_pk_add_f32 v[56:57], v[56:57], v[12:13] neg_lo:[0,1] neg_hi:[0,1]
	s_waitcnt lgkmcnt(8)
	v_mfma_f32_32x32x16_bf16 v[18:33], v[66:69], v[112:115], v[18:33]
	ds_read_b64_tr_b16 v[112:113], v16 offset:22528
	ds_read_b64_tr_b16 v[114:115], v16 offset:23040
	v_pk_add_f32 v[58:59], v[58:59], v[12:13] neg_lo:[0,1] neg_hi:[0,1]
	v_pk_add_f32 v[60:61], v[60:61], v[12:13] neg_lo:[0,1] neg_hi:[0,1]
	v_pk_add_f32 v[62:63], v[62:63], v[12:13] neg_lo:[0,1] neg_hi:[0,1]
	v_pk_add_f32 v[64:65], v[64:65], v[12:13] neg_lo:[0,1] neg_hi:[0,1]
	v_exp_f32_e32 v50, v50
	v_exp_f32_e32 v51, v51
	v_exp_f32_e32 v52, v52
	v_exp_f32_e32 v53, v53
	v_exp_f32_e32 v54, v54
	s_waitcnt lgkmcnt(8)
	v_mfma_f32_32x32x16_bf16 v[34:49], v[74:77], v[120:123], v[34:49]
	ds_read_b64_tr_b16 v[120:121], v16 offset:19456
	ds_read_b64_tr_b16 v[122:123], v16 offset:19968
	v_exp_f32_e32 v55, v55
	v_exp_f32_e32 v56, v56
	v_exp_f32_e32 v57, v57
	v_exp_f32_e32 v58, v58
	v_exp_f32_e32 v59, v59
	v_exp_f32_e32 v60, v60
	s_waitcnt lgkmcnt(8)
	v_mfma_f32_32x32x16_bf16 v[18:33], v[74:77], v[70:73], v[18:33]
	v_exp_f32_e32 v61, v61
	v_exp_f32_e32 v62, v62
	v_exp_f32_e32 v63, v63
	v_exp_f32_e32 v64, v64
	v_exp_f32_e32 v65, v65
	v_pk_add_f32 v[14:15], v[14:15], v[50:51]
	v_pk_add_f32 v[14:15], v[14:15], v[52:53]
	v_pk_add_f32 v[14:15], v[14:15], v[54:55]
	v_pk_add_f32 v[14:15], v[14:15], v[56:57]
	v_cvt_pk_bf16_f32 v50, v50, v51
	v_cvt_pk_bf16_f32 v51, v52, v53
	v_cvt_pk_bf16_f32 v52, v54, v55
	v_cvt_pk_bf16_f32 v53, v56, v57
	v_pk_add_f32 v[14:15], v[14:15], v[58:59]
	v_pk_add_f32 v[14:15], v[14:15], v[60:61]
	s_waitcnt lgkmcnt(6)
	v_mfma_f32_32x32x16_bf16 v[34:49], v[50:53], v[78:81], v[34:49]
	v_pk_add_f32 v[14:15], v[14:15], v[62:63]
	v_pk_add_f32 v[14:15], v[14:15], v[64:65]
	v_cvt_pk_bf16_f32 v58, v58, v59
	v_cvt_pk_bf16_f32 v59, v60, v61
	v_cvt_pk_bf16_f32 v60, v62, v63
	v_cvt_pk_bf16_f32 v61, v64, v65
	v_add_f32_e32 v11, v11, v14
	v_add_f32_e32 v11, v11, v15
	v_mov_b32_e32 v106, v11
	v_mov_b32_e32 v107, v2
	s_waitcnt lgkmcnt(2)
	v_mfma_f32_32x32x16_bf16 v[18:33], v[50:53], v[112:115], v[18:33]
	s_waitcnt lgkmcnt(0)
	v_mfma_f32_32x32x16_bf16 v[34:49], v[58:61], v[120:123], v[34:49]
	v_mfma_f32_32x32x16_bf16 v[18:33], v[58:61], v[108:111], v[18:33]
	s_mov_b32 s100, s101
	s_andn2_b64 exec, exec, s[14:15]
	s_cbranch_execz .LBB0_1188
.LBB0_1181:
	s_and_b32 s16, s6, 0x2000
	s_add_i32 s28, s16, 0
	v_add3_u32 v2, s28, v220, v221
	s_waitcnt vmcnt(0) lgkmcnt(0)
	ds_write_b128 v2, v[98:101]
	v_add_u32_e32 v2, s28, v247
	s_cmp_eq_u64 s[98:99], 0
	s_cselect_b64 s[80:81], -1, 0
	s_cselect_b64 vcc, 0, -1
	ds_write_b128 v2, v[102:105] offset:16384
	s_waitcnt lgkmcnt(0)
	s_barrier
	s_and_saveexec_b64 s[16:17], vcc
	s_cbranch_execz .LBB0_1183
	s_ff1_i32_b64 s101, s[98:99]
	s_add_u32 s82, s98, -1
	s_addc_u32 s83, s99, -1
	s_and_b64 s[98:99], s[98:99], s[82:83]
	s_lshl_b32 s86, s101, 13
	s_add_u32 s82, s88, s86
	s_addc_u32 s83, s89, 0
	s_add_u32 s86, s90, s86
	s_addc_u32 s87, s91, 0
	global_load_dwordx4 v[98:101], v246, s[82:83]
	global_load_dwordx4 v[102:105], v246, s[86:87]
